# MLA attention: s_setprio 1 raised before the QK LDS fragment reads instead of after them
# baseline (speedup 1.0000x reference)
; #define MFMA(a, b, c) __builtin_amdgcn_mfma_f32_32x32x16_bf16((a), (b), (c), 0, 0, 0)
; DI int crow(int r, int hf) { return (r & 3) + 8 * (r >> 2) + 4 * hf; }
; DI bf16x8 join8(uint2 lo, uint2 hi) { uint4 u = make_uint4(lo.x, lo.y, hi.x, hi.y); return __builtin_bit_cast(bf16x8, u); }
; DI f32x16 zero16() { f32x16 z; for (int i = 0; i < 16; ++i) z[i] = 0.f; return z; }
; DI void mla_item(const Params& p, int qb, int b, int h, char* smem) {
;     ...
;   auto compute = [&](int kt, int sub) {
;     const char* sk = smem + (kt & 1) * MLA_BUF2 + sub * (64 * 208); const char* sv = smem + (kt & 1) * MLA_BUF2 + 128 * 208 + sub * 128;
;     const int k0 = kt * 128 + sub * 64;
;     if (k0 <= q0 + 31) {
;       f32x16 st[2];
;       bf16x8 kf[2][6];
; #pragma unroll
;       for (int t32 = 0; t32 < 2; ++t32)
; #pragma unroll
;         for (int s = 0; s < 6; ++s) kf[t32][s] = *(const bf16x8*)(sk + (t32 * 32 + l32) * 208 + (s * 16 + hf * 8) * 2);
;       __builtin_amdgcn_sched_barrier(0);
;       __builtin_amdgcn_s_setprio(1);
; #pragma unroll
;       for (int t32 = 0; t32 < 2; ++t32) {
;         st[t32] = zero16();
; #pragma unroll
;         for (int s = 0; s < 6; ++s) st[t32] = MFMA(kf[t32][s], qf[s], st[t32]);
;       }
;       __builtin_amdgcn_s_setprio(0);
;       bf16x8 vf[2][2][2];
; #pragma unroll
;       for (int t32 = 0; t32 < 2; ++t32)
; #pragma unroll
;         for (int s = 0; s < 2; ++s)
; #pragma unroll
;           for (int mt = 0; mt < 2; ++mt) {
;             const char* vp = sv + (mt * 32 + l32) * MLA_SVP + (t32 * 32 + s * 16 + hf * 4) * 2;
;             vf[t32][s][mt] = join8(*(const uint2*)vp, *(const uint2*)(vp + 16));
;           }
;       __builtin_amdgcn_sched_barrier(0);
;       if (k0 + 63 > q0) {
;         const int qpos = q0 + l32;
; #pragma unroll
;         for (int t32 = 0; t32 < 2; ++t32)
; #pragma unroll
;           for (int r = 0; r < 16; ++r) { const int key = k0 + t32 * 32 + crow(r, hf); if (key > qpos) st[t32][r] = -1e30f; }
;       }
.LBB0_628:
	s_add_i32 s5, s4, 0xfffffe80
	v_cmp_le_i32_e32 vcc, s5, v220
	v_add_u32_e32 v230, 0x6800, v226
	v_add_u32_e32 v229, 0x8800, v226
	s_and_saveexec_b64 s[8:9], vcc
	s_cbranch_execz .LBB0_632
	s_setprio 1
	ds_read_b128 v[32:35], v225
	ds_read_b128 v[36:39], v225 offset:32
	ds_read_b128 v[40:43], v225 offset:64
	ds_read_b128 v[44:47], v225 offset:96
	ds_read_b128 v[128:131], v225 offset:128
	ds_read_b128 v[132:135], v225 offset:160
	ds_read_b128 v[136:139], v225 offset:6656
	ds_read_b128 v[140:143], v225 offset:6688
	ds_read_b128 v[144:147], v225 offset:6720
	ds_read_b128 v[148:151], v225 offset:6752
	ds_read_b128 v[152:155], v225 offset:6784
	ds_read_b128 v[156:159], v225 offset:6816
	s_waitcnt lgkmcnt(0)
	v_mfma_f32_32x32x16_bf16 v[48:63], v[32:35], v[64:67], 0
	v_mfma_f32_32x32x16_bf16 v[48:63], v[36:39], v[68:71], v[48:63]
	v_mfma_f32_32x32x16_bf16 v[48:63], v[40:43], v[72:75], v[48:63]
	v_mfma_f32_32x32x16_bf16 v[48:63], v[44:47], v[76:79], v[48:63]
	v_mfma_f32_32x32x16_bf16 v[32:47], v[136:139], v[64:67], 0
	v_mfma_f32_32x32x16_bf16 v[32:47], v[140:143], v[68:71], v[32:47]
	v_mfma_f32_32x32x16_bf16 v[32:47], v[144:147], v[72:75], v[32:47]
	v_mfma_f32_32x32x16_bf16 v[32:47], v[148:151], v[76:79], v[32:47]
	v_mfma_f32_32x32x16_bf16 v[48:63], v[128:131], v[80:83], v[48:63]
	v_mfma_f32_32x32x16_bf16 v[32:47], v[152:155], v[80:83], v[32:47]
	v_mfma_f32_32x32x16_bf16 v[48:63], v[132:135], v[84:87], v[48:63]
	v_mfma_f32_32x32x16_bf16 v[32:47], v[156:159], v[84:87], v[32:47]
	s_setprio 0
	ds_read2_b64 v[152:155], v230 offset1:2
	ds_read2_b64 v[144:147], v230 offset0:4 offset1:6
	ds_read2_b64 v[156:159], v229 offset0:32 offset1:34
	ds_read2_b64 v[148:151], v229 offset0:36 offset1:38
	ds_read2_b64 v[136:139], v230 offset0:8 offset1:10
	ds_read2_b64 v[140:143], v229 offset0:40 offset1:42
	ds_read2_b64 v[128:131], v230 offset0:12 offset1:14
	ds_read2_b64 v[132:135], v229 offset0:44 offset1:46
	s_add_i32 s5, s4, 0xfffffebf
	v_cmp_gt_i32_e32 vcc, s5, v168
	s_and_saveexec_b64 s[10:11], vcc
	s_cbranch_execz .LBB0_631
	v_add_u32_e32 v188, s4, v212
	v_add_u32_e32 v189, 0xfffffe80, v188
	v_cmp_lt_i32_e32 vcc, v189, v222
	s_nop 1
	v_cndmask_b32_e32 v49, v187, v49, vcc
	v_cmp_le_i32_e32 vcc, v189, v222
	v_add_u32_e32 v189, 0xfffffe82, v188
	s_nop 0
	v_cndmask_b32_e32 v48, v187, v48, vcc
	v_cmp_le_i32_e32 vcc, v189, v222
	v_add_u32_e32 v189, 0xfffffe83, v188
	s_nop 0
	v_cndmask_b32_e32 v50, v187, v50, vcc
	v_cmp_le_i32_e32 vcc, v189, v222
	v_add_u32_e32 v189, 0xfffffe88, v188
	s_nop 0
	v_cndmask_b32_e32 v51, v187, v51, vcc
	v_cmp_le_i32_e32 vcc, v189, v222
	v_add_u32_e32 v189, 0xfffffe89, v188
	s_nop 0
	v_cndmask_b32_e32 v52, v187, v52, vcc
	v_cmp_le_i32_e32 vcc, v189, v222
	v_add_u32_e32 v189, 0xfffffe8a, v188
	s_nop 0
	v_cndmask_b32_e32 v53, v187, v53, vcc
	v_cmp_le_i32_e32 vcc, v189, v222
	v_add_u32_e32 v189, 0xfffffe8b, v188
	s_nop 0
	v_cndmask_b32_e32 v54, v187, v54, vcc
	v_cmp_le_i32_e32 vcc, v189, v222
	v_add_u32_e32 v189, 0xfffffe90, v188
	s_nop 0
	v_cndmask_b32_e32 v55, v187, v55, vcc
	v_cmp_le_i32_e32 vcc, v189, v222
	v_add_u32_e32 v189, 0xfffffe91, v188
	s_nop 0
	v_cndmask_b32_e32 v56, v187, v56, vcc
	v_cmp_le_i32_e32 vcc, v189, v222
	v_add_u32_e32 v189, 0xfffffe92, v188
	s_nop 0
	v_cndmask_b32_e32 v57, v187, v57, vcc
	v_cmp_le_i32_e32 vcc, v189, v222
	v_add_u32_e32 v189, 0xfffffe93, v188
	s_nop 0
	v_cndmask_b32_e32 v58, v187, v58, vcc
	v_cmp_le_i32_e32 vcc, v189, v222
	v_add_u32_e32 v189, 0xfffffe98, v188
	s_nop 0
	v_cndmask_b32_e32 v59, v187, v59, vcc
	v_cmp_le_i32_e32 vcc, v189, v222
	v_add_u32_e32 v189, 0xfffffe99, v188
	s_nop 0
	v_cndmask_b32_e32 v60, v187, v60, vcc
	v_cmp_le_i32_e32 vcc, v189, v222
	v_add_u32_e32 v189, 0xfffffe9a, v188
	s_nop 0
	v_cndmask_b32_e32 v61, v187, v61, vcc
	v_cmp_le_i32_e32 vcc, v189, v222
	v_add_u32_e32 v189, 0xfffffe9b, v188
	s_nop 0
	v_cndmask_b32_e32 v62, v187, v62, vcc
	v_cmp_le_i32_e32 vcc, v189, v222
	v_add_u32_e32 v189, 0xfffffea0, v188
	s_nop 0
	v_cndmask_b32_e32 v63, v187, v63, vcc
	v_cmp_le_i32_e32 vcc, v189, v222
	v_add_u32_e32 v189, 0xfffffea1, v188
	s_nop 0
	v_cndmask_b32_e32 v32, v187, v32, vcc
	v_cmp_le_i32_e32 vcc, v189, v222
	v_add_u32_e32 v189, 0xfffffea2, v188
	s_nop 0
	v_cndmask_b32_e32 v33, v187, v33, vcc
	v_cmp_le_i32_e32 vcc, v189, v222
	v_add_u32_e32 v189, 0xfffffea3, v188
	s_nop 0
	v_cndmask_b32_e32 v34, v187, v34, vcc
	v_cmp_le_i32_e32 vcc, v189, v222
	v_add_u32_e32 v189, 0xfffffea8, v188
	s_nop 0
	v_cndmask_b32_e32 v35, v187, v35, vcc
	v_cmp_le_i32_e32 vcc, v189, v222
	v_add_u32_e32 v189, 0xfffffea9, v188
	s_nop 0
	v_cndmask_b32_e32 v36, v187, v36, vcc
	v_cmp_le_i32_e32 vcc, v189, v222
	v_add_u32_e32 v189, 0xfffffeaa, v188
	s_nop 0
	v_cndmask_b32_e32 v37, v187, v37, vcc
	v_cmp_le_i32_e32 vcc, v189, v222
	v_add_u32_e32 v189, 0xfffffeab, v188
	s_nop 0
	v_cndmask_b32_e32 v38, v187, v38, vcc
	v_cmp_le_i32_e32 vcc, v189, v222
	v_add_u32_e32 v189, 0xfffffeb0, v188
	s_nop 0
	v_cndmask_b32_e32 v39, v187, v39, vcc
	v_cmp_le_i32_e32 vcc, v189, v222
	v_add_u32_e32 v189, 0xfffffeb1, v188
	s_nop 0
	v_cndmask_b32_e32 v40, v187, v40, vcc
	v_cmp_le_i32_e32 vcc, v189, v222
	v_add_u32_e32 v189, 0xfffffeb2, v188
	s_nop 0
	v_cndmask_b32_e32 v41, v187, v41, vcc
	v_cmp_le_i32_e32 vcc, v189, v222
	v_add_u32_e32 v189, 0xfffffeb3, v188
	s_nop 0
	v_cndmask_b32_e32 v42, v187, v42, vcc
	v_cmp_le_i32_e32 vcc, v189, v222
	v_add_u32_e32 v189, 0xfffffeb8, v188
	s_nop 0
	v_cndmask_b32_e32 v43, v187, v43, vcc
	v_cmp_le_i32_e32 vcc, v189, v222
	v_add_u32_e32 v189, 0xfffffeb9, v188
	s_nop 0
	v_cndmask_b32_e32 v44, v187, v44, vcc
	v_cmp_le_i32_e32 vcc, v189, v222
	v_add_u32_e32 v189, 0xfffffeba, v188
	v_add_u32_e32 v188, 0xfffffebb, v188
	v_cndmask_b32_e32 v45, v187, v45, vcc
	v_cmp_le_i32_e32 vcc, v189, v222
	s_nop 1
	v_cndmask_b32_e32 v46, v187, v46, vcc
	v_cmp_le_i32_e32 vcc, v188, v222
	s_nop 1
	v_cndmask_b32_e32 v47, v187, v47, vcc

; #define MFMA(a, b, c) __builtin_amdgcn_mfma_f32_32x32x16_bf16((a), (b), (c), 0, 0, 0)
; DI int crow(int r, int hf) { return (r & 3) + 8 * (r >> 2) + 4 * hf; }
; DI bf16x8 join8(uint2 lo, uint2 hi) { uint4 u = make_uint4(lo.x, lo.y, hi.x, hi.y); return __builtin_bit_cast(bf16x8, u); }
; DI f32x16 zero16() { f32x16 z; for (int i = 0; i < 16; ++i) z[i] = 0.f; return z; }
; DI void mla_item(const Params& p, int qb, int b, int h, char* smem) {
;     ...
;   auto compute = [&](int kt, int sub) {
;     const char* sk = smem + (kt & 1) * MLA_BUF2 + sub * (64 * 208); const char* sv = smem + (kt & 1) * MLA_BUF2 + 128 * 208 + sub * 128;
;     const int k0 = kt * 128 + sub * 64;
;     if (k0 <= q0 + 31) {
;       f32x16 st[2];
;       bf16x8 kf[2][6];
; #pragma unroll
;       for (int t32 = 0; t32 < 2; ++t32)
; #pragma unroll
;         for (int s = 0; s < 6; ++s) kf[t32][s] = *(const bf16x8*)(sk + (t32 * 32 + l32) * 208 + (s * 16 + hf * 8) * 2);
;       __builtin_amdgcn_sched_barrier(0);
;       __builtin_amdgcn_s_setprio(1);
; #pragma unroll
;       for (int t32 = 0; t32 < 2; ++t32) {
;         st[t32] = zero16();
; #pragma unroll
;         for (int s = 0; s < 6; ++s) st[t32] = MFMA(kf[t32][s], qf[s], st[t32]);
;       }
;       __builtin_amdgcn_s_setprio(0);
;       bf16x8 vf[2][2][2];
; #pragma unroll
;       for (int t32 = 0; t32 < 2; ++t32)
; #pragma unroll
;         for (int s = 0; s < 2; ++s)
; #pragma unroll
;           for (int mt = 0; mt < 2; ++mt) {
;             const char* vp = sv + (mt * 32 + l32) * MLA_SVP + (t32 * 32 + s * 16 + hf * 4) * 2;
;             vf[t32][s][mt] = join8(*(const uint2*)vp, *(const uint2*)(vp + 16));
;           }
;       __builtin_amdgcn_sched_barrier(0);
;       if (k0 + 63 > q0) {
;         const int qpos = q0 + l32;
; #pragma unroll
;         for (int t32 = 0; t32 < 2; ++t32)
; #pragma unroll
;           for (int r = 0; r < 16; ++r) { const int key = k0 + t32 * 32 + crow(r, hf); if (key > qpos) st[t32][r] = -1e30f; }
;       }
.LBB0_632:
	s_or_b64 exec, exec, s[8:9]
	s_add_i32 s5, s4, 0xfffffec0
	v_cmp_le_i32_e32 vcc, s5, v220
	s_and_saveexec_b64 s[8:9], vcc
	s_cbranch_execz .LBB0_636
	s_setprio 1
	ds_read_b128 v[32:35], v225 offset:13312
	ds_read_b128 v[36:39], v225 offset:13344
	ds_read_b128 v[40:43], v225 offset:13376
	ds_read_b128 v[44:47], v225 offset:13408
	ds_read_b128 v[128:131], v225 offset:13440
	ds_read_b128 v[132:135], v225 offset:13472
	ds_read_b128 v[136:139], v225 offset:19968
	ds_read_b128 v[140:143], v225 offset:20000
	ds_read_b128 v[144:147], v225 offset:20032
	ds_read_b128 v[148:151], v225 offset:20064
	ds_read_b128 v[152:155], v225 offset:20096
	ds_read_b128 v[156:159], v225 offset:20128
	s_waitcnt lgkmcnt(0)
	v_mfma_f32_32x32x16_bf16 v[48:63], v[32:35], v[64:67], 0
	v_mfma_f32_32x32x16_bf16 v[48:63], v[36:39], v[68:71], v[48:63]
	v_mfma_f32_32x32x16_bf16 v[48:63], v[40:43], v[72:75], v[48:63]
	v_mfma_f32_32x32x16_bf16 v[48:63], v[44:47], v[76:79], v[48:63]
	v_mfma_f32_32x32x16_bf16 v[32:47], v[136:139], v[64:67], 0
	v_mfma_f32_32x32x16_bf16 v[32:47], v[140:143], v[68:71], v[32:47]
	v_mfma_f32_32x32x16_bf16 v[32:47], v[144:147], v[72:75], v[32:47]
	v_mfma_f32_32x32x16_bf16 v[32:47], v[148:151], v[76:79], v[32:47]
	v_mfma_f32_32x32x16_bf16 v[48:63], v[128:131], v[80:83], v[48:63]
	v_mfma_f32_32x32x16_bf16 v[32:47], v[152:155], v[80:83], v[32:47]
	v_mfma_f32_32x32x16_bf16 v[48:63], v[132:135], v[84:87], v[48:63]
	v_mfma_f32_32x32x16_bf16 v[32:47], v[156:159], v[84:87], v[32:47]
	s_setprio 0
	ds_read2_b64 v[152:155], v230 offset0:16 offset1:18
	ds_read2_b64 v[144:147], v230 offset0:20 offset1:22
	ds_read2_b64 v[156:159], v229 offset0:48 offset1:50
	ds_read2_b64 v[148:151], v229 offset0:52 offset1:54
	ds_read2_b64 v[136:139], v230 offset0:24 offset1:26
	ds_read2_b64 v[140:143], v229 offset0:56 offset1:58
	ds_read2_b64 v[128:131], v230 offset0:28 offset1:30
	ds_read2_b64 v[132:135], v229 offset0:60 offset1:62
	s_add_i32 s5, s4, 0xfffffeff
	v_cmp_gt_i32_e32 vcc, s5, v168
	s_and_saveexec_b64 s[10:11], vcc
	s_cbranch_execz .LBB0_635
	v_add_u32_e32 v188, s4, v212
	v_add_u32_e32 v189, 0xfffffec0, v188
	v_cmp_le_i32_e32 vcc, v189, v222
	v_add_u32_e32 v189, 0xfffffec1, v188
	s_nop 0
	v_cndmask_b32_e32 v48, v187, v48, vcc
	v_cmp_le_i32_e32 vcc, v189, v222
	v_add_u32_e32 v189, 0xfffffec2, v188
	s_nop 0
	v_cndmask_b32_e32 v49, v187, v49, vcc
	v_cmp_le_i32_e32 vcc, v189, v222
	v_add_u32_e32 v189, 0xfffffec3, v188
	s_nop 0
	v_cndmask_b32_e32 v50, v187, v50, vcc
	v_cmp_le_i32_e32 vcc, v189, v222
	v_add_u32_e32 v189, 0xfffffec8, v188
	s_nop 0
	v_cndmask_b32_e32 v51, v187, v51, vcc
	v_cmp_le_i32_e32 vcc, v189, v222
	v_add_u32_e32 v189, 0xfffffec9, v188
	s_nop 0
	v_cndmask_b32_e32 v52, v187, v52, vcc
	v_cmp_le_i32_e32 vcc, v189, v222
	v_add_u32_e32 v189, 0xfffffeca, v188
	s_nop 0
	v_cndmask_b32_e32 v53, v187, v53, vcc
	v_cmp_le_i32_e32 vcc, v189, v222
	v_add_u32_e32 v189, 0xfffffecb, v188
	s_nop 0
	v_cndmask_b32_e32 v54, v187, v54, vcc
	v_cmp_le_i32_e32 vcc, v189, v222
	v_add_u32_e32 v189, 0xfffffed0, v188
	s_nop 0
	v_cndmask_b32_e32 v55, v187, v55, vcc
	v_cmp_le_i32_e32 vcc, v189, v222
	v_add_u32_e32 v189, 0xfffffed1, v188
	s_nop 0
	v_cndmask_b32_e32 v56, v187, v56, vcc
	v_cmp_le_i32_e32 vcc, v189, v222
	v_add_u32_e32 v189, 0xfffffed2, v188
	s_nop 0
	v_cndmask_b32_e32 v57, v187, v57, vcc
	v_cmp_le_i32_e32 vcc, v189, v222
	v_add_u32_e32 v189, 0xfffffed3, v188
	s_nop 0
	v_cndmask_b32_e32 v58, v187, v58, vcc
	v_cmp_le_i32_e32 vcc, v189, v222
	v_add_u32_e32 v189, 0xfffffed8, v188
	s_nop 0
	v_cndmask_b32_e32 v59, v187, v59, vcc
	v_cmp_le_i32_e32 vcc, v189, v222
	v_add_u32_e32 v189, 0xfffffed9, v188
	s_nop 0
	v_cndmask_b32_e32 v60, v187, v60, vcc
	v_cmp_le_i32_e32 vcc, v189, v222
	v_add_u32_e32 v189, 0xfffffeda, v188
	s_nop 0
	v_cndmask_b32_e32 v61, v187, v61, vcc
	v_cmp_le_i32_e32 vcc, v189, v222
	v_add_u32_e32 v189, 0xfffffedb, v188
	s_nop 0
	v_cndmask_b32_e32 v62, v187, v62, vcc
	v_cmp_le_i32_e32 vcc, v189, v222
	v_add_u32_e32 v189, 0xfffffee0, v188
	s_nop 0
	v_cndmask_b32_e32 v63, v187, v63, vcc
	v_cmp_le_i32_e32 vcc, v189, v222
	v_add_u32_e32 v189, 0xfffffee1, v188
	s_nop 0
	v_cndmask_b32_e32 v32, v187, v32, vcc
	v_cmp_le_i32_e32 vcc, v189, v222
	v_add_u32_e32 v189, 0xfffffee2, v188
	s_nop 0
	v_cndmask_b32_e32 v33, v187, v33, vcc
	v_cmp_le_i32_e32 vcc, v189, v222
	v_add_u32_e32 v189, 0xfffffee3, v188
	s_nop 0
	v_cndmask_b32_e32 v34, v187, v34, vcc
	v_cmp_le_i32_e32 vcc, v189, v222
	v_add_u32_e32 v189, 0xfffffee8, v188
	s_nop 0
	v_cndmask_b32_e32 v35, v187, v35, vcc
	v_cmp_le_i32_e32 vcc, v189, v222
	v_add_u32_e32 v189, 0xfffffee9, v188
	s_nop 0
	v_cndmask_b32_e32 v36, v187, v36, vcc
	v_cmp_le_i32_e32 vcc, v189, v222
	v_add_u32_e32 v189, 0xfffffeea, v188
	s_nop 0
	v_cndmask_b32_e32 v37, v187, v37, vcc
	v_cmp_le_i32_e32 vcc, v189, v222
	v_add_u32_e32 v189, 0xfffffeeb, v188
	s_nop 0
	v_cndmask_b32_e32 v38, v187, v38, vcc
	v_cmp_le_i32_e32 vcc, v189, v222
	v_add_u32_e32 v189, 0xfffffef0, v188
	s_nop 0
	v_cndmask_b32_e32 v39, v187, v39, vcc
	v_cmp_le_i32_e32 vcc, v189, v222
	v_add_u32_e32 v189, 0xfffffef1, v188
	s_nop 0
	v_cndmask_b32_e32 v40, v187, v40, vcc
	v_cmp_le_i32_e32 vcc, v189, v222
	v_add_u32_e32 v189, 0xfffffef2, v188
	s_nop 0
	v_cndmask_b32_e32 v41, v187, v41, vcc
	v_cmp_le_i32_e32 vcc, v189, v222
	v_add_u32_e32 v189, 0xfffffef3, v188
	s_nop 0
	v_cndmask_b32_e32 v42, v187, v42, vcc
	v_cmp_le_i32_e32 vcc, v189, v222
	v_add_u32_e32 v189, 0xfffffef8, v188
	s_nop 0
	v_cndmask_b32_e32 v43, v187, v43, vcc
	v_cmp_le_i32_e32 vcc, v189, v222
	v_add_u32_e32 v189, 0xfffffef9, v188
	s_nop 0
	v_cndmask_b32_e32 v44, v187, v44, vcc
	v_cmp_le_i32_e32 vcc, v189, v222
	v_add_u32_e32 v189, 0xfffffefa, v188
	v_add_u32_e32 v188, 0xfffffefb, v188
	v_cndmask_b32_e32 v45, v187, v45, vcc
	v_cmp_le_i32_e32 vcc, v189, v222
	s_nop 1
	v_cndmask_b32_e32 v46, v187, v46, vcc
	v_cmp_le_i32_e32 vcc, v188, v222
	s_nop 1
	v_cndmask_b32_e32 v47, v187, v47, vcc

; #define MFMA(a, b, c) __builtin_amdgcn_mfma_f32_32x32x16_bf16((a), (b), (c), 0, 0, 0)
; DI int crow(int r, int hf) { return (r & 3) + 8 * (r >> 2) + 4 * hf; }
; DI bf16x8 join8(uint2 lo, uint2 hi) { uint4 u = make_uint4(lo.x, lo.y, hi.x, hi.y); return __builtin_bit_cast(bf16x8, u); }
; DI f32x16 zero16() { f32x16 z; for (int i = 0; i < 16; ++i) z[i] = 0.f; return z; }
; DI void mla_item(const Params& p, int qb, int b, int h, char* smem) {
;     ...
;     const char* sk = smem + (kt & 1) * MLA_BUF2 + sub * (64 * 208); const char* sv = smem + (kt & 1) * MLA_BUF2 + 128 * 208 + sub * 128;
;     const int k0 = kt * 128 + sub * 64;
;     if (k0 <= q0 + 31) {
;       f32x16 st[2];
;       bf16x8 kf[2][6];
; #pragma unroll
;       for (int t32 = 0; t32 < 2; ++t32)
; #pragma unroll
;         for (int s = 0; s < 6; ++s) kf[t32][s] = *(const bf16x8*)(sk + (t32 * 32 + l32) * 208 + (s * 16 + hf * 8) * 2);
;       __builtin_amdgcn_sched_barrier(0);
;       __builtin_amdgcn_s_setprio(1);
; #pragma unroll
;       for (int t32 = 0; t32 < 2; ++t32) {
;         st[t32] = zero16();
; #pragma unroll
;         for (int s = 0; s < 6; ++s) st[t32] = MFMA(kf[t32][s], qf[s], st[t32]);
;       }
;       __builtin_amdgcn_s_setprio(0);
;       bf16x8 vf[2][2][2];
; #pragma unroll
;       for (int t32 = 0; t32 < 2; ++t32)
; #pragma unroll
;         for (int s = 0; s < 2; ++s)
; #pragma unroll
;           for (int mt = 0; mt < 2; ++mt) {
;             const char* vp = sv + (mt * 32 + l32) * MLA_SVP + (t32 * 32 + s * 16 + hf * 4) * 2;
;             vf[t32][s][mt] = join8(*(const uint2*)vp, *(const uint2*)(vp + 16));
;           }
;       __builtin_amdgcn_sched_barrier(0);
;       if (k0 + 63 > q0) {
;         const int qpos = q0 + l32;
; #pragma unroll
;         for (int t32 = 0; t32 < 2; ++t32)
; #pragma unroll
;           for (int r = 0; r < 16; ++r) { const int key = k0 + t32 * 32 + crow(r, hf); if (key > qpos) st[t32][r] = -1e30f; }
.LBB0_638:
	s_add_i32 s5, s4, 0xffffff00
	v_cmp_le_i32_e32 vcc, s5, v220
	s_and_saveexec_b64 s[8:9], vcc
	s_cbranch_execz .LBB0_642
	s_setprio 1
	ds_read_b128 v[32:35], v225 offset:43520
	ds_read_b128 v[36:39], v225 offset:43552
	ds_read_b128 v[40:43], v225 offset:43584
	ds_read_b128 v[44:47], v225 offset:43616
	ds_read_b128 v[128:131], v225 offset:43648
	ds_read_b128 v[132:135], v225 offset:43680
	ds_read_b128 v[136:139], v225 offset:50176
	ds_read_b128 v[140:143], v225 offset:50208
	ds_read_b128 v[144:147], v225 offset:50240
	ds_read_b128 v[148:151], v225 offset:50272
	ds_read_b128 v[152:155], v225 offset:50304
	ds_read_b128 v[156:159], v225 offset:50336
	s_waitcnt lgkmcnt(0)
	v_mfma_f32_32x32x16_bf16 v[48:63], v[32:35], v[64:67], 0
	v_mfma_f32_32x32x16_bf16 v[48:63], v[36:39], v[68:71], v[48:63]
	v_mfma_f32_32x32x16_bf16 v[48:63], v[40:43], v[72:75], v[48:63]
	v_mfma_f32_32x32x16_bf16 v[48:63], v[44:47], v[76:79], v[48:63]
	v_mfma_f32_32x32x16_bf16 v[32:47], v[136:139], v[64:67], 0
	v_mfma_f32_32x32x16_bf16 v[32:47], v[140:143], v[68:71], v[32:47]
	v_mfma_f32_32x32x16_bf16 v[32:47], v[144:147], v[72:75], v[32:47]
	v_mfma_f32_32x32x16_bf16 v[32:47], v[148:151], v[76:79], v[32:47]
	v_mfma_f32_32x32x16_bf16 v[48:63], v[128:131], v[80:83], v[48:63]
	v_mfma_f32_32x32x16_bf16 v[32:47], v[152:155], v[80:83], v[32:47]
	v_mfma_f32_32x32x16_bf16 v[48:63], v[132:135], v[84:87], v[48:63]
	v_mfma_f32_32x32x16_bf16 v[32:47], v[156:159], v[84:87], v[32:47]
	s_setprio 0
	v_add_u32_e32 v132, 0x2000, v223
	ds_read2_b64 v[152:155], v223 offset1:2
	ds_read2_b64 v[144:147], v223 offset0:4 offset1:6
	ds_read2_b64 v[156:159], v132 offset0:32 offset1:34
	ds_read2_b64 v[148:151], v132 offset0:36 offset1:38
	ds_read2_b64 v[136:139], v223 offset0:8 offset1:10
	ds_read2_b64 v[140:143], v132 offset0:40 offset1:42
	ds_read2_b64 v[128:131], v223 offset0:12 offset1:14
	ds_read2_b64 v[132:135], v132 offset0:44 offset1:46
	s_add_i32 s5, s4, 0xffffff3f
	v_cmp_gt_i32_e32 vcc, s5, v168
	s_and_saveexec_b64 s[10:11], vcc
	s_cbranch_execz .LBB0_641
	v_add_u32_e32 v188, s4, v212
	v_add_u32_e32 v189, 0xffffff00, v188
	v_cmp_lt_i32_e32 vcc, v189, v222
	s_nop 1
	v_cndmask_b32_e32 v49, v187, v49, vcc
	v_cmp_le_i32_e32 vcc, v189, v222
	v_add_u32_e32 v189, 0xffffff02, v188
	s_nop 0
	v_cndmask_b32_e32 v48, v187, v48, vcc
	v_cmp_le_i32_e32 vcc, v189, v222
	v_add_u32_e32 v189, 0xffffff03, v188
	s_nop 0
	v_cndmask_b32_e32 v50, v187, v50, vcc
	v_cmp_le_i32_e32 vcc, v189, v222
	v_add_u32_e32 v189, 0xffffff08, v188
	s_nop 0
	v_cndmask_b32_e32 v51, v187, v51, vcc
	v_cmp_le_i32_e32 vcc, v189, v222
	v_add_u32_e32 v189, 0xffffff09, v188
	s_nop 0
	v_cndmask_b32_e32 v52, v187, v52, vcc
	v_cmp_le_i32_e32 vcc, v189, v222
	v_add_u32_e32 v189, 0xffffff0a, v188
	s_nop 0
	v_cndmask_b32_e32 v53, v187, v53, vcc
	v_cmp_le_i32_e32 vcc, v189, v222
	v_add_u32_e32 v189, 0xffffff0b, v188
	s_nop 0
	v_cndmask_b32_e32 v54, v187, v54, vcc
	v_cmp_le_i32_e32 vcc, v189, v222
	v_add_u32_e32 v189, 0xffffff10, v188
	s_nop 0
	v_cndmask_b32_e32 v55, v187, v55, vcc
	v_cmp_le_i32_e32 vcc, v189, v222
	v_add_u32_e32 v189, 0xffffff11, v188
	s_nop 0
	v_cndmask_b32_e32 v56, v187, v56, vcc
	v_cmp_le_i32_e32 vcc, v189, v222
	v_add_u32_e32 v189, 0xffffff12, v188
	s_nop 0
	v_cndmask_b32_e32 v57, v187, v57, vcc
	v_cmp_le_i32_e32 vcc, v189, v222
	v_add_u32_e32 v189, 0xffffff13, v188
	s_nop 0
	v_cndmask_b32_e32 v58, v187, v58, vcc
	v_cmp_le_i32_e32 vcc, v189, v222
	v_add_u32_e32 v189, 0xffffff18, v188
	s_nop 0
	v_cndmask_b32_e32 v59, v187, v59, vcc
	v_cmp_le_i32_e32 vcc, v189, v222
	v_add_u32_e32 v189, 0xffffff19, v188
	s_nop 0
	v_cndmask_b32_e32 v60, v187, v60, vcc
	v_cmp_le_i32_e32 vcc, v189, v222
	v_add_u32_e32 v189, 0xffffff1a, v188
	s_nop 0
	v_cndmask_b32_e32 v61, v187, v61, vcc
	v_cmp_le_i32_e32 vcc, v189, v222
	v_add_u32_e32 v189, 0xffffff1b, v188
	s_nop 0
	v_cndmask_b32_e32 v62, v187, v62, vcc
	v_cmp_le_i32_e32 vcc, v189, v222
	v_add_u32_e32 v189, 0xffffff20, v188
	s_nop 0
	v_cndmask_b32_e32 v63, v187, v63, vcc
	v_cmp_le_i32_e32 vcc, v189, v222
	v_add_u32_e32 v189, 0xffffff21, v188
	s_nop 0
	v_cndmask_b32_e32 v32, v187, v32, vcc
	v_cmp_le_i32_e32 vcc, v189, v222
	v_add_u32_e32 v189, 0xffffff22, v188
	s_nop 0
	v_cndmask_b32_e32 v33, v187, v33, vcc
	v_cmp_le_i32_e32 vcc, v189, v222
	v_add_u32_e32 v189, 0xffffff23, v188
	s_nop 0
	v_cndmask_b32_e32 v34, v187, v34, vcc
	v_cmp_le_i32_e32 vcc, v189, v222
	v_add_u32_e32 v189, 0xffffff28, v188
	s_nop 0
	v_cndmask_b32_e32 v35, v187, v35, vcc
	v_cmp_le_i32_e32 vcc, v189, v222
	v_add_u32_e32 v189, 0xffffff29, v188
	s_nop 0
	v_cndmask_b32_e32 v36, v187, v36, vcc
	v_cmp_le_i32_e32 vcc, v189, v222
	v_add_u32_e32 v189, 0xffffff2a, v188
	s_nop 0
	v_cndmask_b32_e32 v37, v187, v37, vcc
	v_cmp_le_i32_e32 vcc, v189, v222
	v_add_u32_e32 v189, 0xffffff2b, v188
	s_nop 0
	v_cndmask_b32_e32 v38, v187, v38, vcc
	v_cmp_le_i32_e32 vcc, v189, v222
	v_add_u32_e32 v189, 0xffffff30, v188
	s_nop 0
	v_cndmask_b32_e32 v39, v187, v39, vcc
	v_cmp_le_i32_e32 vcc, v189, v222
	v_add_u32_e32 v189, 0xffffff31, v188
	s_nop 0
	v_cndmask_b32_e32 v40, v187, v40, vcc
	v_cmp_le_i32_e32 vcc, v189, v222
	v_add_u32_e32 v189, 0xffffff32, v188
	s_nop 0
	v_cndmask_b32_e32 v41, v187, v41, vcc
	v_cmp_le_i32_e32 vcc, v189, v222
	v_add_u32_e32 v189, 0xffffff33, v188
	s_nop 0
	v_cndmask_b32_e32 v42, v187, v42, vcc
	v_cmp_le_i32_e32 vcc, v189, v222
	v_add_u32_e32 v189, 0xffffff38, v188
	s_nop 0
	v_cndmask_b32_e32 v43, v187, v43, vcc
	v_cmp_le_i32_e32 vcc, v189, v222
	v_add_u32_e32 v189, 0xffffff39, v188
	s_nop 0
	v_cndmask_b32_e32 v44, v187, v44, vcc
	v_cmp_le_i32_e32 vcc, v189, v222
	v_add_u32_e32 v189, 0xffffff3a, v188
	v_add_u32_e32 v188, 0xffffff3b, v188
	v_cndmask_b32_e32 v45, v187, v45, vcc
	v_cmp_le_i32_e32 vcc, v189, v222
	s_nop 1
	v_cndmask_b32_e32 v46, v187, v46, vcc
	v_cmp_le_i32_e32 vcc, v188, v222
	s_nop 1
	v_cndmask_b32_e32 v47, v187, v47, vcc

; #define MFMA(a, b, c) __builtin_amdgcn_mfma_f32_32x32x16_bf16((a), (b), (c), 0, 0, 0)
; DI int crow(int r, int hf) { return (r & 3) + 8 * (r >> 2) + 4 * hf; }
; DI bf16x8 join8(uint2 lo, uint2 hi) { uint4 u = make_uint4(lo.x, lo.y, hi.x, hi.y); return __builtin_bit_cast(bf16x8, u); }
; DI f32x16 zero16() { f32x16 z; for (int i = 0; i < 16; ++i) z[i] = 0.f; return z; }
; DI void mla_item(const Params& p, int qb, int b, int h, char* smem) {
;     ...
;     const char* sk = smem + (kt & 1) * MLA_BUF2 + sub * (64 * 208); const char* sv = smem + (kt & 1) * MLA_BUF2 + 128 * 208 + sub * 128;
;     const int k0 = kt * 128 + sub * 64;
;     if (k0 <= q0 + 31) {
;       f32x16 st[2];
;       bf16x8 kf[2][6];
; #pragma unroll
;       for (int t32 = 0; t32 < 2; ++t32)
; #pragma unroll
;         for (int s = 0; s < 6; ++s) kf[t32][s] = *(const bf16x8*)(sk + (t32 * 32 + l32) * 208 + (s * 16 + hf * 8) * 2);
;       __builtin_amdgcn_sched_barrier(0);
;       __builtin_amdgcn_s_setprio(1);
; #pragma unroll
;       for (int t32 = 0; t32 < 2; ++t32) {
;         st[t32] = zero16();
; #pragma unroll
;         for (int s = 0; s < 6; ++s) st[t32] = MFMA(kf[t32][s], qf[s], st[t32]);
;       }
;       __builtin_amdgcn_s_setprio(0);
;       bf16x8 vf[2][2][2];
; #pragma unroll
;       for (int t32 = 0; t32 < 2; ++t32)
; #pragma unroll
;         for (int s = 0; s < 2; ++s)
; #pragma unroll
;           for (int mt = 0; mt < 2; ++mt) {
;             const char* vp = sv + (mt * 32 + l32) * MLA_SVP + (t32 * 32 + s * 16 + hf * 4) * 2;
;             vf[t32][s][mt] = join8(*(const uint2*)vp, *(const uint2*)(vp + 16));
;           }
;       __builtin_amdgcn_sched_barrier(0);
;       if (k0 + 63 > q0) {
;         const int qpos = q0 + l32;
; #pragma unroll
;         for (int t32 = 0; t32 < 2; ++t32)
; #pragma unroll
;           for (int r = 0; r < 16; ++r) { const int key = k0 + t32 * 32 + crow(r, hf); if (key > qpos) st[t32][r] = -1e30f; }
.LBB0_642:
	s_or_b64 exec, exec, s[8:9]
	s_add_i32 s5, s4, 0xffffff40
	v_cmp_le_i32_e32 vcc, s5, v220
	s_and_saveexec_b64 s[8:9], vcc
	s_cbranch_execz .LBB0_646
	s_setprio 1
	ds_read_b128 v[32:35], v225 offset:56832
	ds_read_b128 v[36:39], v225 offset:56864
	ds_read_b128 v[40:43], v225 offset:56896
	ds_read_b128 v[44:47], v225 offset:56928
	ds_read_b128 v[128:131], v225 offset:56960
	ds_read_b128 v[132:135], v225 offset:56992
	ds_read_b128 v[136:139], v225 offset:63488
	ds_read_b128 v[140:143], v225 offset:63520
	ds_read_b128 v[144:147], v225 offset:63552
	ds_read_b128 v[148:151], v225 offset:63584
	ds_read_b128 v[152:155], v225 offset:63616
	ds_read_b128 v[156:159], v225 offset:63648
	s_waitcnt lgkmcnt(0)
	v_mfma_f32_32x32x16_bf16 v[48:63], v[32:35], v[64:67], 0
	v_mfma_f32_32x32x16_bf16 v[48:63], v[36:39], v[68:71], v[48:63]
	v_mfma_f32_32x32x16_bf16 v[48:63], v[40:43], v[72:75], v[48:63]
	v_mfma_f32_32x32x16_bf16 v[48:63], v[44:47], v[76:79], v[48:63]
	v_mfma_f32_32x32x16_bf16 v[32:47], v[136:139], v[64:67], 0
	v_mfma_f32_32x32x16_bf16 v[32:47], v[140:143], v[68:71], v[32:47]
	v_mfma_f32_32x32x16_bf16 v[32:47], v[144:147], v[72:75], v[32:47]
	v_mfma_f32_32x32x16_bf16 v[32:47], v[148:151], v[76:79], v[32:47]
	v_mfma_f32_32x32x16_bf16 v[48:63], v[128:131], v[80:83], v[48:63]
	v_mfma_f32_32x32x16_bf16 v[32:47], v[152:155], v[80:83], v[32:47]
	v_mfma_f32_32x32x16_bf16 v[48:63], v[132:135], v[84:87], v[48:63]
	v_mfma_f32_32x32x16_bf16 v[32:47], v[156:159], v[84:87], v[32:47]
	s_setprio 0
	v_add_u32_e32 v132, 0x2000, v224
	ds_read2_b64 v[152:155], v224 offset1:2
	ds_read2_b64 v[144:147], v224 offset0:4 offset1:6
	ds_read2_b64 v[156:159], v132 offset0:32 offset1:34
	ds_read2_b64 v[148:151], v132 offset0:36 offset1:38
	ds_read2_b64 v[136:139], v224 offset0:8 offset1:10
	ds_read2_b64 v[140:143], v132 offset0:40 offset1:42
	ds_read2_b64 v[128:131], v224 offset0:12 offset1:14
	ds_read2_b64 v[132:135], v132 offset0:44 offset1:46
	s_add_i32 s5, s4, 0xffffff7f
	v_cmp_gt_i32_e32 vcc, s5, v168
	s_and_saveexec_b64 s[10:11], vcc
	s_cbranch_execz .LBB0_645
	v_add_u32_e32 v188, s4, v212
	v_add_u32_e32 v189, 0xffffff40, v188
	v_cmp_le_i32_e32 vcc, v189, v222
	v_add_u32_e32 v189, 0xffffff41, v188
	s_nop 0
	v_cndmask_b32_e32 v48, v187, v48, vcc
	v_cmp_le_i32_e32 vcc, v189, v222
	v_add_u32_e32 v189, 0xffffff42, v188
	s_nop 0
	v_cndmask_b32_e32 v49, v187, v49, vcc
	v_cmp_le_i32_e32 vcc, v189, v222
	v_add_u32_e32 v189, 0xffffff43, v188
	s_nop 0
	v_cndmask_b32_e32 v50, v187, v50, vcc
	v_cmp_le_i32_e32 vcc, v189, v222
	v_add_u32_e32 v189, 0xffffff48, v188
	s_nop 0
	v_cndmask_b32_e32 v51, v187, v51, vcc
	v_cmp_le_i32_e32 vcc, v189, v222
	v_add_u32_e32 v189, 0xffffff49, v188
	s_nop 0
	v_cndmask_b32_e32 v52, v187, v52, vcc
	v_cmp_le_i32_e32 vcc, v189, v222
	v_add_u32_e32 v189, 0xffffff4a, v188
	s_nop 0
	v_cndmask_b32_e32 v53, v187, v53, vcc
	v_cmp_le_i32_e32 vcc, v189, v222
	v_add_u32_e32 v189, 0xffffff4b, v188
	s_nop 0
	v_cndmask_b32_e32 v54, v187, v54, vcc
	v_cmp_le_i32_e32 vcc, v189, v222
	v_add_u32_e32 v189, 0xffffff50, v188
	s_nop 0
	v_cndmask_b32_e32 v55, v187, v55, vcc
	v_cmp_le_i32_e32 vcc, v189, v222
	v_add_u32_e32 v189, 0xffffff51, v188
	s_nop 0
	v_cndmask_b32_e32 v56, v187, v56, vcc
	v_cmp_le_i32_e32 vcc, v189, v222
	v_add_u32_e32 v189, 0xffffff52, v188
	s_nop 0
	v_cndmask_b32_e32 v57, v187, v57, vcc
	v_cmp_le_i32_e32 vcc, v189, v222
	v_add_u32_e32 v189, 0xffffff53, v188
	s_nop 0
	v_cndmask_b32_e32 v58, v187, v58, vcc
	v_cmp_le_i32_e32 vcc, v189, v222
	v_add_u32_e32 v189, 0xffffff58, v188
	s_nop 0
	v_cndmask_b32_e32 v59, v187, v59, vcc
	v_cmp_le_i32_e32 vcc, v189, v222
	v_add_u32_e32 v189, 0xffffff59, v188
	s_nop 0
	v_cndmask_b32_e32 v60, v187, v60, vcc
	v_cmp_le_i32_e32 vcc, v189, v222
	v_add_u32_e32 v189, 0xffffff5a, v188
	s_nop 0
	v_cndmask_b32_e32 v61, v187, v61, vcc
	v_cmp_le_i32_e32 vcc, v189, v222
	v_add_u32_e32 v189, 0xffffff5b, v188
	s_nop 0
	v_cndmask_b32_e32 v62, v187, v62, vcc
	v_cmp_le_i32_e32 vcc, v189, v222
	v_add_u32_e32 v189, 0xffffff60, v188
	s_nop 0
	v_cndmask_b32_e32 v63, v187, v63, vcc
	v_cmp_le_i32_e32 vcc, v189, v222
	v_add_u32_e32 v189, 0xffffff61, v188
	s_nop 0
	v_cndmask_b32_e32 v32, v187, v32, vcc
	v_cmp_le_i32_e32 vcc, v189, v222
	v_add_u32_e32 v189, 0xffffff62, v188
	s_nop 0
	v_cndmask_b32_e32 v33, v187, v33, vcc
	v_cmp_le_i32_e32 vcc, v189, v222
	v_add_u32_e32 v189, 0xffffff63, v188
	s_nop 0
	v_cndmask_b32_e32 v34, v187, v34, vcc
	v_cmp_le_i32_e32 vcc, v189, v222
	v_add_u32_e32 v189, 0xffffff68, v188
	s_nop 0
	v_cndmask_b32_e32 v35, v187, v35, vcc
	v_cmp_le_i32_e32 vcc, v189, v222
	v_add_u32_e32 v189, 0xffffff69, v188
	s_nop 0
	v_cndmask_b32_e32 v36, v187, v36, vcc
	v_cmp_le_i32_e32 vcc, v189, v222
	v_add_u32_e32 v189, 0xffffff6a, v188
	s_nop 0
	v_cndmask_b32_e32 v37, v187, v37, vcc
	v_cmp_le_i32_e32 vcc, v189, v222
	v_add_u32_e32 v189, 0xffffff6b, v188
	s_nop 0
	v_cndmask_b32_e32 v38, v187, v38, vcc
	v_cmp_le_i32_e32 vcc, v189, v222
	v_add_u32_e32 v189, 0xffffff70, v188
	s_nop 0
	v_cndmask_b32_e32 v39, v187, v39, vcc
	v_cmp_le_i32_e32 vcc, v189, v222
	v_add_u32_e32 v189, 0xffffff71, v188
	s_nop 0
	v_cndmask_b32_e32 v40, v187, v40, vcc
	v_cmp_le_i32_e32 vcc, v189, v222
	v_add_u32_e32 v189, 0xffffff72, v188
	s_nop 0
	v_cndmask_b32_e32 v41, v187, v41, vcc
	v_cmp_le_i32_e32 vcc, v189, v222
	v_add_u32_e32 v189, 0xffffff73, v188
	s_nop 0
	v_cndmask_b32_e32 v42, v187, v42, vcc
	v_cmp_le_i32_e32 vcc, v189, v222
	v_add_u32_e32 v189, 0xffffff78, v188
	s_nop 0
	v_cndmask_b32_e32 v43, v187, v43, vcc
	v_cmp_le_i32_e32 vcc, v189, v222
	v_add_u32_e32 v189, 0xffffff79, v188
	s_nop 0
	v_cndmask_b32_e32 v44, v187, v44, vcc
	v_cmp_le_i32_e32 vcc, v189, v222
	v_add_u32_e32 v189, 0xffffff7a, v188
	v_add_u32_e32 v188, 0xffffff7b, v188
	v_cndmask_b32_e32 v45, v187, v45, vcc
	v_cmp_le_i32_e32 vcc, v189, v222
	s_nop 1
	v_cndmask_b32_e32 v46, v187, v46, vcc
	v_cmp_le_i32_e32 vcc, v188, v222
	s_nop 1
	v_cndmask_b32_e32 v47, v187, v47, vcc
